# lever 2 on ssd_out_item: the 64 conditional decay blocks read SC/DT from a VGPR table preloaded with ds_read_b128 (4 loads per item) instead of 2 ds_read_b32 + waits per block; same arithmetic and mas
# baseline (speedup 1.0000x reference)
.LBB0_1029:
	s_andn2_saveexec_b64 s[6:7], s[6:7]
	s_movk_i32 s3, 0x210
	v_mad_u64_u32 v[6:7], s[8:9], v7, s3, v[40:41]
	s_or_b64 exec, exec, s[6:7]
	s_ashr_i32 s3, s2, 1
	s_and_b32 s3, s3, 0xffffff80
	s_add_i32 s3, s3, 0
	s_add_i32 s6, s3, 0x10800
	v_add_u32_e32 v37, s6, v36
	s_movk_i32 s6, 0x110
	v_mad_u32_u24 v22, v41, s6, v37
	s_waitcnt vmcnt(0)
	ds_write_b128 v6, v[2:5]
	s_waitcnt lgkmcnt(0)
	s_barrier
	ds_read_b128 v[2:5], v22
	v_mul_u32_u24_e32 v6, 0x110, v174
	s_add_i32 s3, s3, 0x14c00
	v_add3_u32 v26, s3, v6, v36
	ds_read_b128 v[150:153], v26
	s_waitcnt lgkmcnt(0)
	v_mfma_f32_32x32x16_bf16 v[2:17], v[2:5], v[150:153], 0
	ds_read_b128 v[18:21], v22 offset:32
	ds_read_b128 v[146:149], v26 offset:32
	s_lshl_b32 s3, s4, 2
	s_add_i32 s3, s3, 0
	v_lshlrev_b32_e32 v176, 2, v72
	v_cmp_le_u32_e32 vcc, v176, v174
	s_waitcnt lgkmcnt(0)
	v_mfma_f32_32x32x16_bf16 v[2:17], v[18:21], v[146:149], v[2:17]
	ds_read_b128 v[18:21], v22 offset:64
	ds_read_b128 v[142:145], v26 offset:64
	ds_read_b128 v[22:25], v22 offset:96
	ds_read_b128 v[138:141], v26 offset:96
	s_waitcnt lgkmcnt(2)
	v_mfma_f32_32x32x16_bf16 v[2:17], v[18:21], v[142:145], v[2:17]
	v_lshl_add_u32 v18, v174, 2, s3
	v_add_u32_e32 v18, 0x19000, v18
	ds_read2st64_b32 v[172:173], v18 offset1:4
	v_mov_b32_e32 v19, 0
	v_mov_b32_e32 v18, 0
	s_waitcnt lgkmcnt(1)
	v_mfma_f32_32x32x16_bf16 v[2:17], v[22:25], v[138:141], v[2:17]
	v_or_b32_e32 v187, s4, v176
	v_lshl_add_u32 v187, v187, 2, 0
	v_add_u32_e32 v187, 0x19000, v187
	ds_read_b128 v[204:207], v187
	ds_read_b128 v[208:211], v187 offset:32
	ds_read_b128 v[212:215], v187 offset:2048
	ds_read_b128 v[216:219], v187 offset:2080
	ds_read_b128 v[230:233], v187 offset:1024
	ds_read_b128 v[234:237], v187 offset:1056
	ds_read_b128 v[238:241], v187 offset:3072
	ds_read_b128 v[242:245], v187 offset:3104
	s_waitcnt lgkmcnt(0)
	s_and_saveexec_b64 s[6:7], vcc
	s_cbranch_execz .LBB0_1033
	s_waitcnt lgkmcnt(1)
	v_sub_f32_e32 v20, v172, v204
	v_mul_f32_e32 v20, 0x3fb8aa3b, v20
	v_exp_f32_e32 v20, v20
	s_waitcnt lgkmcnt(0)
	v_mul_f32_e32 v18, v212, v20
.LBB0_1033:
	s_or_b64 exec, exec, s[6:7]
	s_add_i32 s3, s4, 0x100
	v_cmp_lt_u32_e32 vcc, v176, v174
	v_cmp_ge_u32_e64 s[40:41], v176, v174
	v_mov_b32_e32 v20, 0
	s_and_saveexec_b64 s[6:7], s[40:41]
	s_cbranch_execz .LBB0_1035
	s_waitcnt lgkmcnt(1)
	v_sub_f32_e32 v21, v173, v230
	v_mul_f32_e32 v21, 0x3fb8aa3b, v21
	v_exp_f32_e32 v21, v21
	s_waitcnt lgkmcnt(0)
	v_mul_f32_e32 v20, v238, v21
.LBB0_1035:
	s_or_b64 exec, exec, s[6:7]
	v_or_b32_e32 v23, 1, v176
	s_and_saveexec_b64 s[6:7], vcc
	s_cbranch_execz .LBB0_1037
	s_waitcnt lgkmcnt(1)
	v_sub_f32_e32 v21, v172, v205
	v_mul_f32_e32 v21, 0x3fb8aa3b, v21
	v_exp_f32_e32 v21, v21
	s_waitcnt lgkmcnt(0)
	v_mul_f32_e32 v19, v213, v21
.LBB0_1037:
	s_or_b64 exec, exec, s[6:7]
	v_cmp_ge_u32_e32 vcc, v23, v174
	v_mov_b32_e32 v22, 0
	v_mov_b32_e32 v21, 0
	s_and_saveexec_b64 s[6:7], vcc
	s_cbranch_execz .LBB0_1039
	s_waitcnt lgkmcnt(1)
	v_sub_f32_e32 v23, v173, v231
	v_mul_f32_e32 v23, 0x3fb8aa3b, v23
	v_exp_f32_e32 v23, v23
	s_waitcnt lgkmcnt(0)
	v_mul_f32_e32 v21, v239, v23
.LBB0_1039:
	s_or_b64 exec, exec, s[6:7]
	v_or_b32_e32 v25, 2, v176
	v_cmp_le_u32_e32 vcc, v25, v174
	s_and_saveexec_b64 s[6:7], vcc
	s_cbranch_execz .LBB0_1041
	s_waitcnt lgkmcnt(1)
	v_sub_f32_e32 v23, v172, v206
	v_mul_f32_e32 v23, 0x3fb8aa3b, v23
	v_exp_f32_e32 v23, v23
	s_waitcnt lgkmcnt(0)
	v_mul_f32_e32 v22, v214, v23
.LBB0_1041:
	s_or_b64 exec, exec, s[6:7]
	v_cmp_ge_u32_e32 vcc, v25, v174
	v_mov_b32_e32 v24, 0
	v_mov_b32_e32 v23, 0
	s_and_saveexec_b64 s[6:7], vcc
	s_cbranch_execz .LBB0_1043
	s_waitcnt lgkmcnt(1)
	v_sub_f32_e32 v25, v173, v232
	v_mul_f32_e32 v25, 0x3fb8aa3b, v25
	v_exp_f32_e32 v25, v25
	s_waitcnt lgkmcnt(0)
	v_mul_f32_e32 v23, v240, v25
.LBB0_1043:
	s_or_b64 exec, exec, s[6:7]
	v_or_b32_e32 v27, 3, v176
	v_cmp_le_u32_e32 vcc, v27, v174
	s_and_saveexec_b64 s[6:7], vcc
	s_cbranch_execz .LBB0_1045
	s_waitcnt lgkmcnt(1)
	v_sub_f32_e32 v25, v172, v207
	v_mul_f32_e32 v25, 0x3fb8aa3b, v25
	v_exp_f32_e32 v25, v25
	s_waitcnt lgkmcnt(0)
	v_mul_f32_e32 v24, v215, v25
.LBB0_1045:
	s_or_b64 exec, exec, s[6:7]
	v_cmp_ge_u32_e32 vcc, v27, v174
	v_mov_b32_e32 v26, 0
	v_mov_b32_e32 v25, 0
	s_and_saveexec_b64 s[6:7], vcc
	s_cbranch_execz .LBB0_1047
	s_waitcnt lgkmcnt(1)
	v_sub_f32_e32 v27, v173, v233
	v_mul_f32_e32 v27, 0x3fb8aa3b, v27
	v_exp_f32_e32 v27, v27
	s_waitcnt lgkmcnt(0)
	v_mul_f32_e32 v25, v241, v27
.LBB0_1047:
	s_or_b64 exec, exec, s[6:7]
	v_or_b32_e32 v29, 8, v176
	v_cmp_le_u32_e32 vcc, v29, v174
	s_and_saveexec_b64 s[6:7], vcc
	s_cbranch_execz .LBB0_1049
	s_waitcnt lgkmcnt(1)
	v_sub_f32_e32 v27, v172, v208
	v_mul_f32_e32 v27, 0x3fb8aa3b, v27
	v_exp_f32_e32 v27, v27
	s_waitcnt lgkmcnt(0)
	v_mul_f32_e32 v26, v216, v27
.LBB0_1049:
	s_or_b64 exec, exec, s[6:7]
	v_cmp_ge_u32_e32 vcc, v29, v174
	v_mov_b32_e32 v28, 0
	v_mov_b32_e32 v27, 0
	s_and_saveexec_b64 s[6:7], vcc
	s_cbranch_execz .LBB0_1051
	s_waitcnt lgkmcnt(1)
	v_sub_f32_e32 v29, v173, v234
	v_mul_f32_e32 v29, 0x3fb8aa3b, v29
	v_exp_f32_e32 v29, v29
	s_waitcnt lgkmcnt(0)
	v_mul_f32_e32 v27, v242, v29
.LBB0_1051:
	s_or_b64 exec, exec, s[6:7]
	v_or_b32_e32 v31, 9, v176
	v_cmp_le_u32_e32 vcc, v31, v174
	s_and_saveexec_b64 s[6:7], vcc
	s_cbranch_execz .LBB0_1053
	s_waitcnt lgkmcnt(1)
	v_sub_f32_e32 v29, v172, v209
	v_mul_f32_e32 v29, 0x3fb8aa3b, v29
	v_exp_f32_e32 v29, v29
	s_waitcnt lgkmcnt(0)
	v_mul_f32_e32 v28, v217, v29
.LBB0_1053:
	s_or_b64 exec, exec, s[6:7]
	v_cmp_ge_u32_e32 vcc, v31, v174
	v_mov_b32_e32 v30, 0
	v_mov_b32_e32 v29, 0
	s_and_saveexec_b64 s[6:7], vcc
	s_cbranch_execz .LBB0_1055
	s_waitcnt lgkmcnt(1)
	v_sub_f32_e32 v31, v173, v235
	v_mul_f32_e32 v31, 0x3fb8aa3b, v31
	v_exp_f32_e32 v31, v31
	s_waitcnt lgkmcnt(0)
	v_mul_f32_e32 v29, v243, v31
.LBB0_1055:
	s_or_b64 exec, exec, s[6:7]
	v_or_b32_e32 v33, 10, v176
	v_cmp_le_u32_e32 vcc, v33, v174
	s_and_saveexec_b64 s[6:7], vcc
	s_cbranch_execz .LBB0_1057
	s_waitcnt lgkmcnt(1)
	v_sub_f32_e32 v31, v172, v210
	v_mul_f32_e32 v31, 0x3fb8aa3b, v31
	v_exp_f32_e32 v31, v31
	s_waitcnt lgkmcnt(0)
	v_mul_f32_e32 v30, v218, v31
.LBB0_1057:
	s_or_b64 exec, exec, s[6:7]
	v_cmp_ge_u32_e32 vcc, v33, v174
	v_mov_b32_e32 v32, 0
	v_mov_b32_e32 v31, 0
	s_and_saveexec_b64 s[6:7], vcc
	s_cbranch_execz .LBB0_1059
	s_waitcnt lgkmcnt(1)
	v_sub_f32_e32 v33, v173, v236
	v_mul_f32_e32 v33, 0x3fb8aa3b, v33
	v_exp_f32_e32 v33, v33
	s_waitcnt lgkmcnt(0)
	v_mul_f32_e32 v31, v244, v33
.LBB0_1059:
	s_or_b64 exec, exec, s[6:7]
	v_or_b32_e32 v38, 11, v176
	v_cmp_le_u32_e32 vcc, v38, v174
	s_and_saveexec_b64 s[6:7], vcc
	s_cbranch_execz .LBB0_1061
	s_waitcnt lgkmcnt(1)
	v_sub_f32_e32 v33, v172, v211
	v_mul_f32_e32 v33, 0x3fb8aa3b, v33
	v_exp_f32_e32 v33, v33
	s_waitcnt lgkmcnt(0)
	v_mul_f32_e32 v32, v219, v33
.LBB0_1061:
	s_or_b64 exec, exec, s[6:7]
	v_cmp_ge_u32_e32 vcc, v38, v174
	v_mov_b32_e32 v36, 0
	v_mov_b32_e32 v33, 0
	s_and_saveexec_b64 s[6:7], vcc
	s_cbranch_execz .LBB0_1063
	s_waitcnt lgkmcnt(1)
	v_sub_f32_e32 v38, v173, v237
	v_mul_f32_e32 v38, 0x3fb8aa3b, v38
	v_exp_f32_e32 v38, v38
	s_waitcnt lgkmcnt(0)
	v_mul_f32_e32 v33, v245, v38
.LBB0_1063:
	s_or_b64 exec, exec, s[6:7]
	v_or_b32_e32 v40, 16, v176
	v_cmp_le_u32_e32 vcc, v40, v174
	v_or_b32_e32 v187, s4, v176
	v_lshl_add_u32 v187, v187, 2, 0
	v_add_u32_e32 v187, 0x19040, v187
	ds_read_b128 v[204:207], v187
	ds_read_b128 v[208:211], v187 offset:32
	ds_read_b128 v[212:215], v187 offset:2048
	ds_read_b128 v[216:219], v187 offset:2080
	ds_read_b128 v[230:233], v187 offset:1024
	ds_read_b128 v[234:237], v187 offset:1056
	ds_read_b128 v[238:241], v187 offset:3072
	ds_read_b128 v[242:245], v187 offset:3104
	s_waitcnt lgkmcnt(0)
	s_and_saveexec_b64 s[6:7], vcc
	s_cbranch_execz .LBB0_1065
	s_waitcnt lgkmcnt(1)
	v_sub_f32_e32 v38, v172, v204
	v_mul_f32_e32 v38, 0x3fb8aa3b, v38
	v_exp_f32_e32 v38, v38
	s_waitcnt lgkmcnt(0)
	v_mul_f32_e32 v36, v212, v38
.LBB0_1065:
	s_or_b64 exec, exec, s[6:7]
	v_cmp_ge_u32_e32 vcc, v40, v174
	v_mov_b32_e32 v39, 0
	v_mov_b32_e32 v38, 0
	s_and_saveexec_b64 s[6:7], vcc
	s_cbranch_execz .LBB0_1067
	s_waitcnt lgkmcnt(1)
	v_sub_f32_e32 v40, v173, v230
	v_mul_f32_e32 v40, 0x3fb8aa3b, v40
	v_exp_f32_e32 v40, v40
	s_waitcnt lgkmcnt(0)
	v_mul_f32_e32 v38, v238, v40
.LBB0_1067:
	s_or_b64 exec, exec, s[6:7]
	v_or_b32_e32 v43, 17, v176
	v_cmp_le_u32_e32 vcc, v43, v174
	s_and_saveexec_b64 s[6:7], vcc
	s_cbranch_execz .LBB0_1069
	s_waitcnt lgkmcnt(1)
	v_sub_f32_e32 v40, v172, v205
	v_mul_f32_e32 v40, 0x3fb8aa3b, v40
	v_exp_f32_e32 v40, v40
	s_waitcnt lgkmcnt(0)
	v_mul_f32_e32 v39, v213, v40
.LBB0_1069:
	s_or_b64 exec, exec, s[6:7]
	v_cmp_ge_u32_e32 vcc, v43, v174
	v_mov_b32_e32 v42, 0
	v_mov_b32_e32 v40, 0
	s_and_saveexec_b64 s[6:7], vcc
	s_cbranch_execz .LBB0_1071
	s_waitcnt lgkmcnt(1)
	v_sub_f32_e32 v43, v173, v231
	v_mul_f32_e32 v43, 0x3fb8aa3b, v43
	v_exp_f32_e32 v43, v43
	s_waitcnt lgkmcnt(0)
	v_mul_f32_e32 v40, v239, v43
.LBB0_1071:
	s_or_b64 exec, exec, s[6:7]
	v_or_b32_e32 v45, 18, v176
	v_cmp_le_u32_e32 vcc, v45, v174
	s_and_saveexec_b64 s[6:7], vcc
	s_cbranch_execz .LBB0_1073
	s_waitcnt lgkmcnt(1)
	v_sub_f32_e32 v43, v172, v206
	v_mul_f32_e32 v43, 0x3fb8aa3b, v43
	v_exp_f32_e32 v43, v43
	s_waitcnt lgkmcnt(0)
	v_mul_f32_e32 v42, v214, v43
.LBB0_1073:
	s_or_b64 exec, exec, s[6:7]
	v_cmp_ge_u32_e32 vcc, v45, v174
	v_mov_b32_e32 v44, 0
	v_mov_b32_e32 v43, 0
	s_and_saveexec_b64 s[6:7], vcc
	s_cbranch_execz .LBB0_1075
	s_waitcnt lgkmcnt(1)
	v_sub_f32_e32 v45, v173, v232
	v_mul_f32_e32 v45, 0x3fb8aa3b, v45
	v_exp_f32_e32 v45, v45
	s_waitcnt lgkmcnt(0)
	v_mul_f32_e32 v43, v240, v45
.LBB0_1075:
	s_or_b64 exec, exec, s[6:7]
	v_or_b32_e32 v47, 19, v176
	v_cmp_le_u32_e32 vcc, v47, v174
	s_and_saveexec_b64 s[6:7], vcc
	s_cbranch_execz .LBB0_1077
	s_waitcnt lgkmcnt(1)
	v_sub_f32_e32 v45, v172, v207
	v_mul_f32_e32 v45, 0x3fb8aa3b, v45
	v_exp_f32_e32 v45, v45
	s_waitcnt lgkmcnt(0)
	v_mul_f32_e32 v44, v215, v45
.LBB0_1077:
	s_or_b64 exec, exec, s[6:7]
	v_cmp_ge_u32_e32 vcc, v47, v174
	v_mov_b32_e32 v46, 0
	v_mov_b32_e32 v45, 0
	s_and_saveexec_b64 s[6:7], vcc
	s_cbranch_execz .LBB0_1079
	s_waitcnt lgkmcnt(1)
	v_sub_f32_e32 v47, v173, v233
	v_mul_f32_e32 v47, 0x3fb8aa3b, v47
	v_exp_f32_e32 v47, v47
	s_waitcnt lgkmcnt(0)
	v_mul_f32_e32 v45, v241, v47
.LBB0_1079:
	s_or_b64 exec, exec, s[6:7]
	v_or_b32_e32 v49, 24, v176
	v_cmp_le_u32_e32 vcc, v49, v174
	s_and_saveexec_b64 s[6:7], vcc
	s_cbranch_execz .LBB0_1081
	s_waitcnt lgkmcnt(1)
	v_sub_f32_e32 v47, v172, v208
	v_mul_f32_e32 v47, 0x3fb8aa3b, v47
	v_exp_f32_e32 v47, v47
	s_waitcnt lgkmcnt(0)
	v_mul_f32_e32 v46, v216, v47
.LBB0_1081:
	s_or_b64 exec, exec, s[6:7]
	v_cmp_ge_u32_e32 vcc, v49, v174
	v_mov_b32_e32 v48, 0
	v_mov_b32_e32 v47, 0
	s_and_saveexec_b64 s[6:7], vcc
	s_cbranch_execz .LBB0_1083
	s_waitcnt lgkmcnt(1)
	v_sub_f32_e32 v49, v173, v234
	v_mul_f32_e32 v49, 0x3fb8aa3b, v49
	v_exp_f32_e32 v49, v49
	s_waitcnt lgkmcnt(0)
	v_mul_f32_e32 v47, v242, v49
.LBB0_1083:
	s_or_b64 exec, exec, s[6:7]
	v_or_b32_e32 v49, 25, v176
	v_cmp_le_u32_e32 vcc, v49, v174
	s_and_saveexec_b64 s[6:7], vcc
	s_cbranch_execz .LBB0_1085
	s_waitcnt lgkmcnt(1)
	v_sub_f32_e32 v66, v172, v209
	v_mul_f32_e32 v66, 0x3fb8aa3b, v66
	v_exp_f32_e32 v66, v66
	s_waitcnt lgkmcnt(0)
	v_mul_f32_e32 v48, v217, v66
.LBB0_1085:
	s_or_b64 exec, exec, s[6:7]
	v_cmp_ge_u32_e32 vcc, v49, v174
	v_mov_b32_e32 v68, 0
	v_mov_b32_e32 v67, 0
	s_and_saveexec_b64 s[6:7], vcc
	s_cbranch_execz .LBB0_1087
	s_waitcnt lgkmcnt(1)
	v_sub_f32_e32 v66, v173, v235
	v_mul_f32_e32 v66, 0x3fb8aa3b, v66
	v_exp_f32_e32 v66, v66
	s_waitcnt lgkmcnt(0)
	v_mul_f32_e32 v67, v243, v66
.LBB0_1087:
	s_or_b64 exec, exec, s[6:7]
	v_or_b32_e32 v66, 26, v176
	v_cmp_le_u32_e32 vcc, v66, v174
	s_and_saveexec_b64 s[6:7], vcc
	s_cbranch_execz .LBB0_1089
	s_waitcnt lgkmcnt(1)
	v_sub_f32_e32 v68, v172, v210
	v_mul_f32_e32 v68, 0x3fb8aa3b, v68
	v_exp_f32_e32 v68, v68
	s_waitcnt lgkmcnt(0)
	v_mul_f32_e32 v68, v218, v68
.LBB0_1089:
	s_or_b64 exec, exec, s[6:7]
	v_cmp_ge_u32_e32 vcc, v66, v174
	v_mov_b32_e32 v49, 0
	v_mov_b32_e32 v70, 0
	s_and_saveexec_b64 s[6:7], vcc
	s_cbranch_execz .LBB0_1091
	s_waitcnt lgkmcnt(1)
	v_sub_f32_e32 v69, v173, v236
	v_mul_f32_e32 v69, 0x3fb8aa3b, v69
	v_exp_f32_e32 v69, v69
	s_waitcnt lgkmcnt(0)
	v_mul_f32_e32 v70, v244, v69
.LBB0_1091:
	s_or_b64 exec, exec, s[6:7]
	v_or_b32_e32 v71, 27, v176
	v_cmp_le_u32_e32 vcc, v71, v174
	s_and_saveexec_b64 s[6:7], vcc
	s_cbranch_execz .LBB0_1093
	s_waitcnt lgkmcnt(1)
	v_sub_f32_e32 v66, v172, v211
	v_mul_f32_e32 v66, 0x3fb8aa3b, v66
	v_exp_f32_e32 v66, v66
	s_waitcnt lgkmcnt(0)
	v_mul_f32_e32 v49, v219, v66
.LBB0_1093:
	s_or_b64 exec, exec, s[6:7]
	v_cmp_ge_u32_e32 vcc, v71, v174
	v_mov_b32_e32 v66, 0
	v_mov_b32_e32 v69, 0
	s_and_saveexec_b64 s[6:7], vcc
	s_cbranch_execz .LBB0_1095
	s_waitcnt lgkmcnt(1)
	v_sub_f32_e32 v71, v173, v237
	v_mul_f32_e32 v71, 0x3fb8aa3b, v71
	v_exp_f32_e32 v71, v71
	s_waitcnt lgkmcnt(0)
	v_mul_f32_e32 v69, v245, v71
.LBB0_1095:
	s_or_b64 exec, exec, s[6:7]
	v_mul_u32_u24_e32 v71, 0x110, v41
	v_add_f32_e32 v41, v68, v70
	v_mul_f32_e32 v41, v16, v41
	v_add_f32_e32 v16, v48, v67
	v_mul_f32_e32 v48, v15, v16
	v_add_f32_e32 v15, v46, v47
	v_mul_f32_e32 v46, v14, v15
	v_add_f32_e32 v14, v44, v45
	v_mul_f32_e32 v44, v13, v14
	v_add_f32_e32 v13, v42, v43
	v_mul_f32_e32 v42, v12, v13
	v_add_f32_e32 v12, v39, v40
	v_mul_f32_e32 v39, v11, v12
	v_add_f32_e32 v11, v36, v38
	v_mul_f32_e32 v36, v10, v11
	v_add_f32_e32 v10, v32, v33
	v_mul_f32_e32 v9, v9, v10
	v_add_f32_e32 v10, v30, v31
	v_mul_f32_e32 v8, v8, v10
	v_add_f32_e32 v10, v28, v29
	v_mul_f32_e32 v7, v7, v10
	v_add_f32_e32 v10, v26, v27
	v_mul_f32_e32 v6, v6, v10
	v_add_f32_e32 v10, v24, v25
	v_mul_f32_e32 v5, v5, v10
	v_add_f32_e32 v10, v22, v23
	v_mul_f32_e32 v4, v4, v10
	v_add_f32_e32 v10, v19, v21
	v_mul_f32_e32 v3, v3, v10
	v_add_f32_e32 v10, v18, v20
	v_mul_f32_e32 v2, v2, v10
	v_lshrrev_b32_e32 v10, 2, v34
	v_and_or_b32 v10, v10, 3, v176
	v_and_or_b32 v11, v34, 16, s4
	v_and_b32_e32 v12, 24, v35
	v_cvt_pk_bf16_f32 v2, v2, v3
	v_cvt_pk_bf16_f32 v3, v4, v5
	v_cvt_pk_bf16_f32 v4, v6, v7
	v_mul_u32_u24_e32 v6, 0x210, v10
	v_lshlrev_b32_e32 v11, 1, v11
	v_add3_u32 v6, 0, v12, v6
	v_add_u32_e32 v67, v6, v11
	v_cvt_pk_bf16_f32 v5, v8, v9
	ds_read_b64_tr_b16 v[6:7], v67
	ds_read_b64_tr_b16 v[8:9], v67 offset:4224
	s_waitcnt lgkmcnt(0)
	v_mfma_f32_32x32x16_bf16 v[18:33], v[6:9], v[2:5], 0
	ds_read_b64_tr_b16 v[6:7], v67 offset:64
	ds_read_b64_tr_b16 v[8:9], v67 offset:4288
	v_cvt_pk_bf16_f32 v38, v36, v39
	v_cvt_pk_bf16_f32 v39, v42, v44
	ds_read_b64_tr_b16 v[42:43], v67 offset:8448
	ds_read_b64_tr_b16 v[44:45], v67 offset:12672
	v_add_f32_e32 v13, v49, v69
	v_mul_f32_e32 v34, v17, v13
	v_cvt_pk_bf16_f32 v40, v46, v48
	s_waitcnt lgkmcnt(2)
	v_mfma_f32_32x32x16_bf16 v[2:17], v[6:9], v[2:5], 0
	v_cvt_pk_bf16_f32 v41, v41, v34
	v_add_u32_e32 v72, v37, v71
	s_waitcnt lgkmcnt(0)
	v_mfma_f32_32x32x16_bf16 v[18:33], v[42:45], v[38:41], v[18:33]
	ds_read_b64_tr_b16 v[42:43], v67 offset:8512
	ds_read_b64_tr_b16 v[44:45], v67 offset:12736
	ds_read_b128 v[34:37], v72 offset:8704
	ds_read_b128 v[68:71], v72 offset:8736
	s_waitcnt lgkmcnt(2)
	v_mfma_f32_32x32x16_bf16 v[2:17], v[42:45], v[38:41], v[2:17]
	s_waitcnt lgkmcnt(1)
	v_mfma_f32_32x32x16_bf16 v[34:49], v[34:37], v[150:153], 0
	s_waitcnt lgkmcnt(0)
	v_mfma_f32_32x32x16_bf16 v[34:49], v[68:71], v[146:149], v[34:49]
	ds_read_b128 v[68:71], v72 offset:8768
	s_waitcnt lgkmcnt(0)
	v_mfma_f32_32x32x16_bf16 v[34:49], v[68:71], v[142:145], v[34:49]
	ds_read_b128 v[68:71], v72 offset:8800
	s_waitcnt lgkmcnt(0)
	v_mfma_f32_32x32x16_bf16 v[34:49], v[68:71], v[138:141], v[34:49]
	v_or_b32_e32 v70, 32, v176
	v_cmp_le_u32_e32 vcc, v70, v174
	v_or_b32_e32 v187, s4, v176
	v_lshl_add_u32 v187, v187, 2, 0
	v_add_u32_e32 v187, 0x19080, v187
	ds_read_b128 v[204:207], v187
	ds_read_b128 v[208:211], v187 offset:32
	ds_read_b128 v[212:215], v187 offset:2048
	ds_read_b128 v[216:219], v187 offset:2080
	ds_read_b128 v[230:233], v187 offset:1024
	ds_read_b128 v[234:237], v187 offset:1056
	ds_read_b128 v[238:241], v187 offset:3072
	ds_read_b128 v[242:245], v187 offset:3104
	s_waitcnt lgkmcnt(0)
	s_and_saveexec_b64 s[6:7], vcc
	s_cbranch_execz .LBB0_1097
	s_waitcnt lgkmcnt(1)
	v_sub_f32_e32 v68, v172, v204
	v_mul_f32_e32 v68, 0x3fb8aa3b, v68
	v_exp_f32_e32 v68, v68
	s_waitcnt lgkmcnt(0)
	v_mul_f32_e32 v66, v212, v68
.LBB0_1097:
	s_or_b64 exec, exec, s[6:7]
	v_cmp_ge_u32_e32 vcc, v70, v174
	v_mov_b32_e32 v69, 0
	v_mov_b32_e32 v68, 0
	s_and_saveexec_b64 s[6:7], vcc
	s_cbranch_execz .LBB0_1099
	s_waitcnt lgkmcnt(1)
	v_sub_f32_e32 v70, v173, v230
	v_mul_f32_e32 v70, 0x3fb8aa3b, v70
	v_exp_f32_e32 v70, v70
	s_waitcnt lgkmcnt(0)
	v_mul_f32_e32 v68, v238, v70
.LBB0_1099:
	s_or_b64 exec, exec, s[6:7]
	v_or_b32_e32 v72, 33, v176
	v_cmp_le_u32_e32 vcc, v72, v174
	s_and_saveexec_b64 s[6:7], vcc
	s_cbranch_execz .LBB0_1101
	s_waitcnt lgkmcnt(1)
	v_sub_f32_e32 v70, v172, v205
	v_mul_f32_e32 v70, 0x3fb8aa3b, v70
	v_exp_f32_e32 v70, v70
	s_waitcnt lgkmcnt(0)
	v_mul_f32_e32 v69, v213, v70
.LBB0_1101:
	s_or_b64 exec, exec, s[6:7]
	v_cmp_ge_u32_e32 vcc, v72, v174
	v_mov_b32_e32 v71, 0
	v_mov_b32_e32 v70, 0
	s_and_saveexec_b64 s[6:7], vcc
	s_cbranch_execz .LBB0_1103
	s_waitcnt lgkmcnt(1)
	v_sub_f32_e32 v72, v173, v231
	v_mul_f32_e32 v72, 0x3fb8aa3b, v72
	v_exp_f32_e32 v72, v72
	s_waitcnt lgkmcnt(0)
	v_mul_f32_e32 v70, v239, v72
.LBB0_1103:
	s_or_b64 exec, exec, s[6:7]
	v_or_b32_e32 v74, 34, v176
	v_cmp_le_u32_e32 vcc, v74, v174
	s_and_saveexec_b64 s[6:7], vcc
	s_cbranch_execz .LBB0_1105
	s_waitcnt lgkmcnt(1)
	v_sub_f32_e32 v72, v172, v206
	v_mul_f32_e32 v72, 0x3fb8aa3b, v72
	v_exp_f32_e32 v72, v72
	s_waitcnt lgkmcnt(0)
	v_mul_f32_e32 v71, v214, v72
.LBB0_1105:
	s_or_b64 exec, exec, s[6:7]
	v_cmp_ge_u32_e32 vcc, v74, v174
	v_mov_b32_e32 v73, 0
	v_mov_b32_e32 v72, 0
	s_and_saveexec_b64 s[6:7], vcc
	s_cbranch_execz .LBB0_1107
	s_waitcnt lgkmcnt(1)
	v_sub_f32_e32 v74, v173, v232
	v_mul_f32_e32 v74, 0x3fb8aa3b, v74
	v_exp_f32_e32 v74, v74
	s_waitcnt lgkmcnt(0)
	v_mul_f32_e32 v72, v240, v74
.LBB0_1107:
	s_or_b64 exec, exec, s[6:7]
	v_or_b32_e32 v76, 35, v176
	v_cmp_le_u32_e32 vcc, v76, v174
	s_and_saveexec_b64 s[6:7], vcc
	s_cbranch_execz .LBB0_1109
	s_waitcnt lgkmcnt(1)
	v_sub_f32_e32 v74, v172, v207
	v_mul_f32_e32 v74, 0x3fb8aa3b, v74
	v_exp_f32_e32 v74, v74
	s_waitcnt lgkmcnt(0)
	v_mul_f32_e32 v73, v215, v74
.LBB0_1109:
	s_or_b64 exec, exec, s[6:7]
	v_cmp_ge_u32_e32 vcc, v76, v174
	v_mov_b32_e32 v75, 0
	v_mov_b32_e32 v74, 0
	s_and_saveexec_b64 s[6:7], vcc
	s_cbranch_execz .LBB0_1111
	s_waitcnt lgkmcnt(1)
	v_sub_f32_e32 v76, v173, v233
	v_mul_f32_e32 v76, 0x3fb8aa3b, v76
	v_exp_f32_e32 v76, v76
	s_waitcnt lgkmcnt(0)
	v_mul_f32_e32 v74, v241, v76
.LBB0_1111:
	s_or_b64 exec, exec, s[6:7]
	v_or_b32_e32 v78, 40, v176
	v_cmp_le_u32_e32 vcc, v78, v174
	s_and_saveexec_b64 s[6:7], vcc
	s_cbranch_execz .LBB0_1113
	s_waitcnt lgkmcnt(1)
	v_sub_f32_e32 v76, v172, v208
	v_mul_f32_e32 v76, 0x3fb8aa3b, v76
	v_exp_f32_e32 v76, v76
	s_waitcnt lgkmcnt(0)
	v_mul_f32_e32 v75, v216, v76
.LBB0_1113:
	s_or_b64 exec, exec, s[6:7]
	v_cmp_ge_u32_e32 vcc, v78, v174
	v_mov_b32_e32 v77, 0
	v_mov_b32_e32 v76, 0
	s_and_saveexec_b64 s[6:7], vcc
	s_cbranch_execz .LBB0_1115
	s_waitcnt lgkmcnt(1)
	v_sub_f32_e32 v78, v173, v234
	v_mul_f32_e32 v78, 0x3fb8aa3b, v78
	v_exp_f32_e32 v78, v78
	s_waitcnt lgkmcnt(0)
	v_mul_f32_e32 v76, v242, v78
.LBB0_1115:
	s_or_b64 exec, exec, s[6:7]
	v_or_b32_e32 v80, 41, v176
	v_cmp_le_u32_e32 vcc, v80, v174
	s_and_saveexec_b64 s[6:7], vcc
	s_cbranch_execz .LBB0_1117
	s_waitcnt lgkmcnt(1)
	v_sub_f32_e32 v78, v172, v209
	v_mul_f32_e32 v78, 0x3fb8aa3b, v78
	v_exp_f32_e32 v78, v78
	s_waitcnt lgkmcnt(0)
	v_mul_f32_e32 v77, v217, v78
.LBB0_1117:
	s_or_b64 exec, exec, s[6:7]
	v_cmp_ge_u32_e32 vcc, v80, v174
	v_mov_b32_e32 v79, 0
	v_mov_b32_e32 v78, 0
	s_and_saveexec_b64 s[6:7], vcc
	s_cbranch_execz .LBB0_1119
	s_waitcnt lgkmcnt(1)
	v_sub_f32_e32 v80, v173, v235
	v_mul_f32_e32 v80, 0x3fb8aa3b, v80
	v_exp_f32_e32 v80, v80
	s_waitcnt lgkmcnt(0)
	v_mul_f32_e32 v78, v243, v80
.LBB0_1119:
	s_or_b64 exec, exec, s[6:7]
	v_or_b32_e32 v82, 42, v176
	v_cmp_le_u32_e32 vcc, v82, v174
	s_and_saveexec_b64 s[6:7], vcc
	s_cbranch_execz .LBB0_1121
	s_waitcnt lgkmcnt(1)
	v_sub_f32_e32 v80, v172, v210
	v_mul_f32_e32 v80, 0x3fb8aa3b, v80
	v_exp_f32_e32 v80, v80
	s_waitcnt lgkmcnt(0)
	v_mul_f32_e32 v79, v218, v80
.LBB0_1121:
	s_or_b64 exec, exec, s[6:7]
	v_cmp_ge_u32_e32 vcc, v82, v174
	v_mov_b32_e32 v81, 0
	v_mov_b32_e32 v80, 0
	s_and_saveexec_b64 s[6:7], vcc
	s_cbranch_execz .LBB0_1123
	s_waitcnt lgkmcnt(1)
	v_sub_f32_e32 v82, v173, v236
	v_mul_f32_e32 v82, 0x3fb8aa3b, v82
	v_exp_f32_e32 v82, v82
	s_waitcnt lgkmcnt(0)
	v_mul_f32_e32 v80, v244, v82
.LBB0_1123:
	s_or_b64 exec, exec, s[6:7]
	v_or_b32_e32 v84, 43, v176
	v_cmp_le_u32_e32 vcc, v84, v174
	s_and_saveexec_b64 s[6:7], vcc
	s_cbranch_execz .LBB0_1125
	s_waitcnt lgkmcnt(1)
	v_sub_f32_e32 v82, v172, v211
	v_mul_f32_e32 v82, 0x3fb8aa3b, v82
	v_exp_f32_e32 v82, v82
	s_waitcnt lgkmcnt(0)
	v_mul_f32_e32 v81, v219, v82
.LBB0_1125:
	s_or_b64 exec, exec, s[6:7]
	v_cmp_ge_u32_e32 vcc, v84, v174
	v_mov_b32_e32 v83, 0
	v_mov_b32_e32 v82, 0
	s_and_saveexec_b64 s[6:7], vcc
	s_cbranch_execz .LBB0_1127
	s_waitcnt lgkmcnt(1)
	v_sub_f32_e32 v84, v173, v237
	v_mul_f32_e32 v84, 0x3fb8aa3b, v84
	v_exp_f32_e32 v84, v84
	s_waitcnt lgkmcnt(0)
	v_mul_f32_e32 v82, v245, v84
.LBB0_1127:
	s_or_b64 exec, exec, s[6:7]
	v_or_b32_e32 v86, 48, v176
	v_cmp_le_u32_e32 vcc, v86, v174
	v_or_b32_e32 v187, s4, v176
	v_lshl_add_u32 v187, v187, 2, 0
	v_add_u32_e32 v187, 0x190c0, v187
	ds_read_b128 v[204:207], v187
	ds_read_b128 v[208:211], v187 offset:32
	ds_read_b128 v[212:215], v187 offset:2048
	ds_read_b128 v[216:219], v187 offset:2080
	ds_read_b128 v[230:233], v187 offset:1024
	ds_read_b128 v[234:237], v187 offset:1056
	ds_read_b128 v[238:241], v187 offset:3072
	ds_read_b128 v[242:245], v187 offset:3104
	s_waitcnt lgkmcnt(0)
	s_and_saveexec_b64 s[6:7], vcc
	s_cbranch_execz .LBB0_1129
	s_waitcnt lgkmcnt(1)
	v_sub_f32_e32 v84, v172, v204
	v_mul_f32_e32 v84, 0x3fb8aa3b, v84
	v_exp_f32_e32 v84, v84
	s_waitcnt lgkmcnt(0)
	v_mul_f32_e32 v83, v212, v84
.LBB0_1129:
	s_or_b64 exec, exec, s[6:7]
	v_cmp_ge_u32_e32 vcc, v86, v174
	v_mov_b32_e32 v85, 0
	v_mov_b32_e32 v84, 0
	s_and_saveexec_b64 s[6:7], vcc
	s_cbranch_execz .LBB0_1131
	s_waitcnt lgkmcnt(1)
	v_sub_f32_e32 v86, v173, v230
	v_mul_f32_e32 v86, 0x3fb8aa3b, v86
	v_exp_f32_e32 v86, v86
	s_waitcnt lgkmcnt(0)
	v_mul_f32_e32 v84, v238, v86
.LBB0_1131:
	s_or_b64 exec, exec, s[6:7]
	v_or_b32_e32 v88, 49, v176
	v_cmp_le_u32_e32 vcc, v88, v174
	s_and_saveexec_b64 s[6:7], vcc
	s_cbranch_execz .LBB0_1133
	s_waitcnt lgkmcnt(1)
	v_sub_f32_e32 v86, v172, v205
	v_mul_f32_e32 v86, 0x3fb8aa3b, v86
	v_exp_f32_e32 v86, v86
	s_waitcnt lgkmcnt(0)
	v_mul_f32_e32 v85, v213, v86
.LBB0_1133:
	s_or_b64 exec, exec, s[6:7]
	v_cmp_ge_u32_e32 vcc, v88, v174
	v_mov_b32_e32 v87, 0
	v_mov_b32_e32 v86, 0
	s_and_saveexec_b64 s[6:7], vcc
	s_cbranch_execz .LBB0_1135
	s_waitcnt lgkmcnt(1)
	v_sub_f32_e32 v88, v173, v231
	v_mul_f32_e32 v88, 0x3fb8aa3b, v88
	v_exp_f32_e32 v88, v88
	s_waitcnt lgkmcnt(0)
	v_mul_f32_e32 v86, v239, v88
.LBB0_1135:
	s_or_b64 exec, exec, s[6:7]
	v_or_b32_e32 v177, 50, v176
	v_cmp_le_u32_e32 vcc, v177, v174
	s_and_saveexec_b64 s[6:7], vcc
	s_cbranch_execz .LBB0_1137
	s_waitcnt lgkmcnt(1)
	v_sub_f32_e32 v88, v172, v206
	v_mul_f32_e32 v88, 0x3fb8aa3b, v88
	v_exp_f32_e32 v88, v88
	s_waitcnt lgkmcnt(0)
	v_mul_f32_e32 v87, v214, v88
.LBB0_1137:
	s_or_b64 exec, exec, s[6:7]
	v_cmp_ge_u32_e32 vcc, v177, v174
	v_mov_b32_e32 v89, 0
	v_mov_b32_e32 v88, 0
	s_and_saveexec_b64 s[6:7], vcc
	s_cbranch_execz .LBB0_1139
	s_waitcnt lgkmcnt(1)
	v_sub_f32_e32 v177, v173, v232
	v_mul_f32_e32 v177, 0x3fb8aa3b, v177
	v_exp_f32_e32 v177, v177
	s_waitcnt lgkmcnt(0)
	v_mul_f32_e32 v88, v240, v177
.LBB0_1139:
	s_or_b64 exec, exec, s[6:7]
	v_or_b32_e32 v179, 51, v176
	v_cmp_le_u32_e32 vcc, v179, v174
	s_and_saveexec_b64 s[6:7], vcc
	s_cbranch_execz .LBB0_1141
	s_waitcnt lgkmcnt(1)
	v_sub_f32_e32 v177, v172, v207
	v_mul_f32_e32 v177, 0x3fb8aa3b, v177
	v_exp_f32_e32 v177, v177
	s_waitcnt lgkmcnt(0)
	v_mul_f32_e32 v89, v215, v177
.LBB0_1141:
	s_or_b64 exec, exec, s[6:7]
	v_cmp_ge_u32_e32 vcc, v179, v174
	v_mov_b32_e32 v178, 0
	v_mov_b32_e32 v177, 0
	s_and_saveexec_b64 s[6:7], vcc
	s_cbranch_execz .LBB0_1143
	s_waitcnt lgkmcnt(1)
	v_sub_f32_e32 v179, v173, v233
	v_mul_f32_e32 v179, 0x3fb8aa3b, v179
	v_exp_f32_e32 v179, v179
	s_waitcnt lgkmcnt(0)
	v_mul_f32_e32 v177, v241, v179
.LBB0_1143:
	s_or_b64 exec, exec, s[6:7]
	v_or_b32_e32 v181, 56, v176
	v_cmp_le_u32_e32 vcc, v181, v174
	s_and_saveexec_b64 s[6:7], vcc
	s_cbranch_execz .LBB0_1145
	s_waitcnt lgkmcnt(1)
	v_sub_f32_e32 v179, v172, v208
	v_mul_f32_e32 v179, 0x3fb8aa3b, v179
	v_exp_f32_e32 v179, v179
	s_waitcnt lgkmcnt(0)
	v_mul_f32_e32 v178, v216, v179
.LBB0_1145:
	s_or_b64 exec, exec, s[6:7]
	v_cmp_ge_u32_e32 vcc, v181, v174
	v_mov_b32_e32 v180, 0
	v_mov_b32_e32 v179, 0
	s_and_saveexec_b64 s[6:7], vcc
	s_cbranch_execz .LBB0_1147
	s_waitcnt lgkmcnt(1)
	v_sub_f32_e32 v181, v173, v234
	v_mul_f32_e32 v181, 0x3fb8aa3b, v181
	v_exp_f32_e32 v181, v181
	s_waitcnt lgkmcnt(0)
	v_mul_f32_e32 v179, v242, v181
.LBB0_1147:
	s_or_b64 exec, exec, s[6:7]
	v_or_b32_e32 v183, 57, v176
	v_cmp_le_u32_e32 vcc, v183, v174
	s_and_saveexec_b64 s[6:7], vcc
	s_cbranch_execz .LBB0_1149
	s_waitcnt lgkmcnt(1)
	v_sub_f32_e32 v181, v172, v209
	v_mul_f32_e32 v181, 0x3fb8aa3b, v181
	v_exp_f32_e32 v181, v181
	s_waitcnt lgkmcnt(0)
	v_mul_f32_e32 v180, v217, v181
.LBB0_1149:
	s_or_b64 exec, exec, s[6:7]
	v_cmp_ge_u32_e32 vcc, v183, v174
	v_mov_b32_e32 v182, 0
	v_mov_b32_e32 v181, 0
	s_and_saveexec_b64 s[6:7], vcc
	s_cbranch_execz .LBB0_1151
	s_waitcnt lgkmcnt(1)
	v_sub_f32_e32 v183, v173, v235
	v_mul_f32_e32 v183, 0x3fb8aa3b, v183
	v_exp_f32_e32 v183, v183
	s_waitcnt lgkmcnt(0)
	v_mul_f32_e32 v181, v243, v183
.LBB0_1151:
	s_or_b64 exec, exec, s[6:7]
	v_or_b32_e32 v185, 58, v176
	v_cmp_le_u32_e32 vcc, v185, v174
	s_and_saveexec_b64 s[6:7], vcc
	s_cbranch_execz .LBB0_1153
	s_waitcnt lgkmcnt(1)
	v_sub_f32_e32 v183, v172, v210
	v_mul_f32_e32 v183, 0x3fb8aa3b, v183
	v_exp_f32_e32 v183, v183
	s_waitcnt lgkmcnt(0)
	v_mul_f32_e32 v182, v218, v183
.LBB0_1153:
	s_or_b64 exec, exec, s[6:7]
	v_cmp_ge_u32_e32 vcc, v185, v174
	v_mov_b32_e32 v183, 0
	v_mov_b32_e32 v184, 0
	s_and_saveexec_b64 s[6:7], vcc
	s_cbranch_execz .LBB0_1155
	s_waitcnt lgkmcnt(1)
	v_sub_f32_e32 v185, v173, v236
	v_mul_f32_e32 v185, 0x3fb8aa3b, v185
	v_exp_f32_e32 v185, v185
	s_waitcnt lgkmcnt(0)
	v_mul_f32_e32 v184, v244, v185
.LBB0_1155:
	s_or_b64 exec, exec, s[6:7]
	v_or_b32_e32 v186, 59, v176
	v_cmp_le_u32_e32 vcc, v186, v174
	s_and_saveexec_b64 s[6:7], vcc
	s_cbranch_execz .LBB0_1157
	s_waitcnt lgkmcnt(1)
	v_sub_f32_e32 v185, v172, v211
	v_mul_f32_e32 v185, 0x3fb8aa3b, v185
	v_exp_f32_e32 v185, v185
	s_waitcnt lgkmcnt(0)
	v_mul_f32_e32 v183, v219, v185
.LBB0_1157:
	s_or_b64 exec, exec, s[6:7]
	v_cmp_ge_u32_e32 vcc, v186, v174
	v_mov_b32_e32 v185, 0
	s_and_saveexec_b64 s[6:7], vcc
	s_cbranch_execz .LBB0_1159
	s_waitcnt lgkmcnt(1)
	v_sub_f32_e32 v186, v173, v237
	v_mul_f32_e32 v186, 0x3fb8aa3b, v186
	v_exp_f32_e32 v186, v186
	s_waitcnt lgkmcnt(0)
	v_mul_f32_e32 v185, v245, v186
